# wa/wb/wo of layer 0 converted in the in-proj L0 idle slot instead of P0 (P0: w_in L0 + x only)
# baseline (speedup 1.0000x reference)
;     ...
;     for (int mi = 0; mi < 7 * DEPTH; ++mi) {
;         if (!((mask >> mi) & 1u)) continue;
;         const int l = mi / 7, kind = mi - 7 * l;
;         const float* W; const float* ks = nullptr; bf16_t* WT; int K, N, rm = 0;
;         if (kind == 0)      { W = a.in[2] + (size_t)l * 2048 * 7680;  K = 2048; N = 7680; WT = (bf16_t*)(ws + WS_WIN + l * SZ_WIN); ks = a.in[1] + l * 2048; rm = 3; }
;         else if (kind == 1) { W = a.in[10] + (size_t)l * 1024 * 2048; K = 1024; N = 2048; WT = (bf16_t*)(ws + WS_WA + l * SZ_WA); }
;         else if (kind == 2) { W = a.in[11] + (size_t)l * 1024 * 2048; K = 1024; N = 2048; WT = (bf16_t*)(ws + WS_WB + l * SZ_WB); }
;         else if (kind == 3) { W = a.in[12] + (size_t)l * 2048 * 2048; K = 2048; N = 2048; WT = (bf16_t*)(ws + WS_WO + l * SZ_WO); }
;         else if (kind == 4) { W = a.in[14] + (size_t)l * 2048 * 5632; K = 2048; N = 5632; WT = (bf16_t*)(ws + WS_WGU + l * SZ_WGU); ks = a.in[13] + l * 2048; rm = 1; }
;         else if (kind == 5) { W = a.in[15] + (size_t)l * 2048 * 5632; K = 2048; N = 5632; WT = (bf16_t*)(ws + WS_WGU + l * SZ_WGU); ks = a.in[13] + l * 2048; rm = 2; }
;         else                { W = a.in[16] + (size_t)l * 5632 * 2048; K = 5632; N = 2048; WT = (bf16_t*)(ws + WS_WD + l * SZ_WD); }
.Lsl_p0_dispatch:
	s_cmp_eq_u32 s46, 0
	s_cbranch_scc1 .Lsl_p0_set0
	s_branch .LBB0_53
.Lsl_p0_set0:
	v_readlane_b32 s22, v250, 6
	v_readlane_b32 s23, v250, 7
	v_readlane_b32 s24, v250, 36
	v_readlane_b32 s25, v250, 37
	v_readlane_b32 s44, v250, 4
	v_readlane_b32 s45, v250, 5
	v_mul_u32_u24_e32 v104, 0x3c000, v102
	v_lshl_add_u32 v104, v103, 4, v104
	v_mul_u32_u24_e32 v105, 0x4000, v103
	v_lshl_add_u32 v105, v102, 4, v105
	s_add_u32 s24, s24, 0x1c0000
	s_addc_u32 s25, s25, 0
	s_mov_b32 s48, 0x7800
	s_mov_b32 s49, 0x1e0000
	s_movk_i32 s50, 8739
	s_mov_b32 s51, 21
	s_movk_i32 s52, 240
	s_movk_i32 s53, 0x1000
	s_mov_b32 s54, 3
	s_mov_b32 s55, 1
	s_movk_i32 s56, 0
	s_movk_i32 s47, 7680
	s_sub_i32 s4, s12, 0
	s_and_b32 s4, s4, 2047
	s_branch .Lsl_p0_loop
.Lsl_p0_loop:
	s_cmp_ge_u32 s4, s47
	s_cbranch_scc1 .Lsl_p0_next
	s_add_i32 s16, s4, s56
	s_mul_i32 s17, s16, s50
	s_lshr_b32 s17, s17, s51
	s_mul_i32 s19, s17, s52
	s_sub_i32 s18, s16, s19
	s_mul_i32 s19, s17, s49
	s_lshl_b32 s20, s18, 7
	s_add_i32 s19, s19, s20
	v_add_u32_e32 v42, s19, v104
	s_cmp_eq_u32 s55, 0
	s_cbranch_scc1 .Lsl_p0_nks1
	s_lshl_b32 s19, s17, 8
	v_add_u32_e32 v43, s19, v110
	global_load_dwordx4 v[34:37], v43, s[44:45]
	global_load_dwordx4 v[38:41], v43, s[44:45] offset:16

;     ...
;     for (int mi = 0; mi < 7 * DEPTH; ++mi) {
;         if (!((mask >> mi) & 1u)) continue;
;         const int l = mi / 7, kind = mi - 7 * l;
;         const float* W; const float* ks = nullptr; bf16_t* WT; int K, N, rm = 0;
;         if (kind == 0)      { W = a.in[2] + (size_t)l * 2048 * 7680;  K = 2048; N = 7680; WT = (bf16_t*)(ws + WS_WIN + l * SZ_WIN); ks = a.in[1] + l * 2048; rm = 3; }
;         else if (kind == 1) { W = a.in[10] + (size_t)l * 1024 * 2048; K = 1024; N = 2048; WT = (bf16_t*)(ws + WS_WA + l * SZ_WA); }
;         else if (kind == 2) { W = a.in[11] + (size_t)l * 1024 * 2048; K = 1024; N = 2048; WT = (bf16_t*)(ws + WS_WB + l * SZ_WB); }
;         else if (kind == 3) { W = a.in[12] + (size_t)l * 2048 * 2048; K = 2048; N = 2048; WT = (bf16_t*)(ws + WS_WO + l * SZ_WO); }
;         else if (kind == 4) { W = a.in[14] + (size_t)l * 2048 * 5632; K = 2048; N = 5632; WT = (bf16_t*)(ws + WS_WGU + l * SZ_WGU); ks = a.in[13] + l * 2048; rm = 1; }
;         else if (kind == 5) { W = a.in[15] + (size_t)l * 2048 * 5632; K = 2048; N = 5632; WT = (bf16_t*)(ws + WS_WGU + l * SZ_WGU); ks = a.in[13] + l * 2048; rm = 2; }
;         else                { W = a.in[16] + (size_t)l * 5632 * 2048; K = 5632; N = 2048; WT = (bf16_t*)(ws + WS_WD + l * SZ_WD); }
; __global__ void __launch_bounds__(NTHREADS, 2) mk_fwd(Args args) {
;     ...
;                 if (blk >= thr) p0_prologue(args, (blk - thr) * NWAVES + wave, (G - thr) * NWAVES, lane, l == 0 ? 0x0030u : 0x1800u, false, l == 0 ? 0x0010u : 0x0800u, 10, 16); }
.Lsl_in_dispatch:
	s_cmp_eq_u32 s28, 0
	s_cbranch_scc1 .Lsl_in_set0
	s_cmp_eq_u32 s28, 1
	s_cbranch_scc1 .Lsl_in_set1
	s_cmp_eq_u32 s28, 2
	s_cbranch_scc1 .Lsl_in_set2
	s_cmp_eq_u32 s28, 3
	s_cbranch_scc1 .Lsl_in_set3
	s_cmp_eq_u32 s28, 4
	s_cbranch_scc1 .Lsl_in_set4
	s_cmp_eq_u32 s28, 16
	s_cbranch_scc1 .Lsl_in_set16
	s_cmp_eq_u32 s28, 17
	s_cbranch_scc1 .Lsl_in_set17
	s_branch .LBB0_256
